# attention step: half of the row-sum adds moved from the QK phase into the first PV MFMA gaps (VALU balanced across MFMA gaps)
# baseline (speedup 1.0000x reference)
.Lat_loop:
	s_cmp_ge_u32 s46, s45
	s_cbranch_scc1 .Lat_drain
	s_lshl_b32 s60, s56, 1
	v_add_u32_e32 v250, s60, v245
	v_mfma_f32_32x32x16_bf16 v[128:143], v[208:211], v[16:19], v[160:175]
	v_add_f32_e32 v247, v247, v96
	v_add_f32_e32 v247, v247, v97
	v_cvt_pk_bf16_f32 v176, v96, v97
	v_cvt_pk_bf16_f32 v177, v98, v99
	v_mfma_f32_32x32x16_bf16 v[144:159], v[212:215], v[16:19], v[160:175]
	v_add_f32_e32 v247, v247, v100
	v_add_f32_e32 v247, v247, v101
	v_cvt_pk_bf16_f32 v178, v100, v101
	v_cvt_pk_bf16_f32 v179, v102, v103
	v_mfma_f32_32x32x16_bf16 v[128:143], v[216:219], v[20:23], v[128:143]
	v_add_f32_e32 v247, v247, v104
	v_add_f32_e32 v247, v247, v105
	v_cvt_pk_bf16_f32 v180, v104, v105
	v_cvt_pk_bf16_f32 v181, v106, v107
	v_mfma_f32_32x32x16_bf16 v[144:159], v[220:223], v[20:23], v[144:159]
	v_add_f32_e32 v247, v247, v108
	v_add_f32_e32 v247, v247, v109
	v_cvt_pk_bf16_f32 v182, v108, v109
	v_cvt_pk_bf16_f32 v183, v110, v111
	v_mfma_f32_32x32x16_bf16 v[128:143], v[224:227], v[24:27], v[128:143]
	v_add_f32_e32 v247, v247, v112
	v_add_f32_e32 v247, v247, v113
	v_cvt_pk_bf16_f32 v184, v112, v113
	v_cvt_pk_bf16_f32 v185, v114, v115
	v_mfma_f32_32x32x16_bf16 v[144:159], v[228:231], v[24:27], v[144:159]
	v_add_f32_e32 v247, v247, v116
	v_add_f32_e32 v247, v247, v117
	v_cvt_pk_bf16_f32 v186, v116, v117
	v_cvt_pk_bf16_f32 v187, v118, v119
	v_mfma_f32_32x32x16_bf16 v[128:143], v[232:235], v[28:31], v[128:143]
	v_add_f32_e32 v247, v247, v120
	v_add_f32_e32 v247, v247, v121
	v_cvt_pk_bf16_f32 v188, v120, v121
	v_cvt_pk_bf16_f32 v189, v122, v123
	ds_read_b64_tr_b16 v[192:193], v250 offset:0
	ds_read_b64_tr_b16 v[194:195], v250 offset:512
	v_mfma_f32_32x32x16_bf16 v[144:159], v[240:243], v[28:31], v[144:159]
	v_add_f32_e32 v247, v247, v124
	v_add_f32_e32 v247, v247, v125
	v_cvt_pk_bf16_f32 v190, v124, v125
	v_cvt_pk_bf16_f32 v191, v126, v127
	ds_read_b64_tr_b16 v[196:197], v250 offset:4096
	ds_read_b64_tr_b16 v[198:199], v250 offset:4608
	s_add_i32 m0, s57, s70
	s_nop 0
	global_load_lds_dwordx4 v238, s[74:75]
	s_add_u32 s74, s74, 0x10000
	s_addc_u32 s75, s75, 0
	s_lshl_b32 s60, s58, 1
	s_add_i32 s60, s60, s71
	s_mov_b32 m0, s60
	s_nop 0
	global_load_lds_dwordx4 v239, s[76:77]
	s_add_u32 s62, s76, 0x80
	s_addc_u32 s63, s77, 0
	s_add_i32 m0, s60, 0x2000
	s_nop 0
	global_load_lds_dwordx4 v239, s[62:63]
	s_add_u32 s76, s76, 0x10000
	s_addc_u32 s77, s77, 0
	s_cmp_lt_u32 s46, s72
	s_cbranch_scc1 .Lat_nomask_504
	s_sub_u32 s60, s46, s72
	s_lshl_b32 s60, s60, 6
	v_lshl_add_u32 v0, v252, 2, s60
	v_sub_u32_e32 v0, v246, v0
	v_mov_b32_e32 v1, 0xff800000
	v_cmp_gt_i32_e64 s[60:61], 0, v0
	v_cmp_gt_i32_e64 s[62:63], 32, v0
	v_cmp_gt_i32_e64 s[64:65], 1, v0
	v_cmp_gt_i32_e64 s[66:67], 33, v0
	v_cndmask_b32_e64 v128, v128, v1, s[60:61]
	v_cmp_gt_i32_e64 s[60:61], 2, v0
	v_cndmask_b32_e64 v144, v144, v1, s[62:63]
	v_cmp_gt_i32_e64 s[62:63], 34, v0
	v_cndmask_b32_e64 v129, v129, v1, s[64:65]
	v_cmp_gt_i32_e64 s[64:65], 3, v0
	v_cndmask_b32_e64 v145, v145, v1, s[66:67]
	v_cmp_gt_i32_e64 s[66:67], 35, v0
	v_cndmask_b32_e64 v130, v130, v1, s[60:61]
	v_cmp_gt_i32_e64 s[60:61], 8, v0
	v_cndmask_b32_e64 v146, v146, v1, s[62:63]
	v_cmp_gt_i32_e64 s[62:63], 40, v0
	v_cndmask_b32_e64 v131, v131, v1, s[64:65]
	v_cmp_gt_i32_e64 s[64:65], 9, v0
	v_cndmask_b32_e64 v147, v147, v1, s[66:67]
	v_cmp_gt_i32_e64 s[66:67], 41, v0
	v_cndmask_b32_e64 v132, v132, v1, s[60:61]
	v_cmp_gt_i32_e64 s[60:61], 10, v0
	v_cndmask_b32_e64 v148, v148, v1, s[62:63]
	v_cmp_gt_i32_e64 s[62:63], 42, v0
	v_cndmask_b32_e64 v133, v133, v1, s[64:65]
	v_cmp_gt_i32_e64 s[64:65], 11, v0
	v_cndmask_b32_e64 v149, v149, v1, s[66:67]
	v_cmp_gt_i32_e64 s[66:67], 43, v0
	v_cndmask_b32_e64 v134, v134, v1, s[60:61]
	v_cmp_gt_i32_e64 s[60:61], 16, v0
	v_cndmask_b32_e64 v150, v150, v1, s[62:63]
	v_cmp_gt_i32_e64 s[62:63], 48, v0
	v_cndmask_b32_e64 v135, v135, v1, s[64:65]
	v_cmp_gt_i32_e64 s[64:65], 17, v0
	v_cndmask_b32_e64 v151, v151, v1, s[66:67]
	v_cmp_gt_i32_e64 s[66:67], 49, v0
	v_cndmask_b32_e64 v136, v136, v1, s[60:61]
	v_cmp_gt_i32_e64 s[60:61], 18, v0
	v_cndmask_b32_e64 v152, v152, v1, s[62:63]
	v_cmp_gt_i32_e64 s[62:63], 50, v0
	v_cndmask_b32_e64 v137, v137, v1, s[64:65]
	v_cmp_gt_i32_e64 s[64:65], 19, v0
	v_cndmask_b32_e64 v153, v153, v1, s[66:67]
	v_cmp_gt_i32_e64 s[66:67], 51, v0
	v_cndmask_b32_e64 v138, v138, v1, s[60:61]
	v_cmp_gt_i32_e64 s[60:61], 24, v0
	v_cndmask_b32_e64 v154, v154, v1, s[62:63]
	v_cmp_gt_i32_e64 s[62:63], 56, v0
	v_cndmask_b32_e64 v139, v139, v1, s[64:65]
	v_cmp_gt_i32_e64 s[64:65], 25, v0
	v_cndmask_b32_e64 v155, v155, v1, s[66:67]
	v_cmp_gt_i32_e64 s[66:67], 57, v0
	v_cndmask_b32_e64 v140, v140, v1, s[60:61]
	v_cmp_gt_i32_e64 s[60:61], 26, v0
	v_cndmask_b32_e64 v156, v156, v1, s[62:63]
	v_cmp_gt_i32_e64 s[62:63], 58, v0
	v_cndmask_b32_e64 v141, v141, v1, s[64:65]
	v_cmp_gt_i32_e64 s[64:65], 27, v0
	v_cndmask_b32_e64 v157, v157, v1, s[66:67]
	v_cmp_gt_i32_e64 s[66:67], 59, v0
	v_cndmask_b32_e64 v142, v142, v1, s[60:61]
	s_nop 1
	v_cndmask_b32_e64 v158, v158, v1, s[62:63]
	v_cndmask_b32_e64 v143, v143, v1, s[64:65]
	v_cndmask_b32_e64 v159, v159, v1, s[66:67]
.Lat_nomask_504:
	ds_read_b64_tr_b16 v[200:201], v250 offset:8192
	ds_read_b64_tr_b16 v[202:203], v250 offset:8704
	ds_read_b64_tr_b16 v[204:205], v250 offset:12288
	ds_read_b64_tr_b16 v[206:207], v250 offset:12800
	s_waitcnt lgkmcnt(4)
	v_mfma_f32_32x32x16_bf16 v[32:47], v[176:179], v[192:195], v[32:47]
	v_max3_f32 v2, v128, v129, v144
	v_max3_f32 v4, v130, v131, v145
	v_max3_f32 v2, v2, v146, v147
	v_add_f32_e32 v247, v247, v98
	v_add_f32_e32 v247, v247, v99
	v_add_f32_e32 v247, v247, v102
	v_mfma_f32_32x32x16_bf16 v[48:63], v[176:179], v[196:199], v[48:63]
	v_max3_f32 v2, v2, v132, v133
	v_max3_f32 v4, v4, v134, v135
	v_max3_f32 v2, v2, v148, v149
	v_add_f32_e32 v247, v247, v103
	v_add_f32_e32 v247, v247, v106
	v_add_f32_e32 v247, v247, v107
	ds_read_b64_tr_b16 v[192:193], v250 offset:1024
	ds_read_b64_tr_b16 v[194:195], v250 offset:1536
	ds_read_b64_tr_b16 v[196:197], v250 offset:5120
	ds_read_b64_tr_b16 v[198:199], v250 offset:5632
	s_waitcnt lgkmcnt(4)
	v_mfma_f32_32x32x16_bf16 v[64:79], v[176:179], v[200:203], v[64:79]
	v_max3_f32 v4, v4, v150, v151
	v_max3_f32 v2, v2, v136, v137
	v_max3_f32 v4, v4, v138, v139
	v_add_f32_e32 v247, v247, v110
	v_add_f32_e32 v247, v247, v111
	v_add_f32_e32 v247, v247, v114
	v_mfma_f32_32x32x16_bf16 v[80:95], v[176:179], v[204:207], v[80:95]
	v_max3_f32 v2, v2, v152, v153
	v_max3_f32 v4, v4, v154, v155
	v_max3_f32 v2, v2, v140, v141
	v_add_f32_e32 v247, v247, v115
	v_add_f32_e32 v247, v247, v118
	v_add_f32_e32 v247, v247, v119
	ds_read_b64_tr_b16 v[200:201], v250 offset:9216
	ds_read_b64_tr_b16 v[202:203], v250 offset:9728
	ds_read_b64_tr_b16 v[204:205], v250 offset:13312
	ds_read_b64_tr_b16 v[206:207], v250 offset:13824
	s_waitcnt lgkmcnt(4)
	v_mfma_f32_32x32x16_bf16 v[32:47], v[180:183], v[192:195], v[32:47]
	v_max3_f32 v4, v4, v142, v143
	v_max3_f32 v2, v2, v156, v157
	v_max3_f32 v4, v4, v158, v159
	v_add_f32_e32 v247, v247, v122
	v_add_f32_e32 v247, v247, v123
	v_mfma_f32_32x32x16_bf16 v[48:63], v[180:183], v[196:199], v[48:63]
	v_max_f32_e32 v2, v2, v4
	v_mov_b32_e32 v4, v2
	s_nop 1
	v_permlane32_swap_b32_e32 v2, v4
	v_max_f32_e32 v2, v2, v4
	v_add_f32_e32 v247, v247, v126
	v_add_f32_e32 v247, v247, v127
	v_mov_b32_e32 v5, 0x41400000
	v_cmp_gt_f32_e32 vcc, v2, v5
	s_mov_b64 s[68:69], vcc
	s_cmp_lg_u64 vcc, 0
	s_cbranch_scc0 .Lat_noresc_439
	v_max_f32_e32 v4, 0, v2
	v_add_f32_e32 v248, v248, v4
	v_sub_f32_e32 v128, v128, v4
	v_sub_f32_e32 v129, v129, v4
	v_sub_f32_e32 v130, v130, v4
	v_sub_f32_e32 v131, v131, v4
	v_sub_f32_e32 v132, v132, v4
	v_sub_f32_e32 v133, v133, v4
	v_sub_f32_e32 v134, v134, v4
	v_sub_f32_e32 v135, v135, v4
	v_sub_f32_e32 v136, v136, v4
	v_sub_f32_e32 v137, v137, v4
	v_sub_f32_e32 v138, v138, v4
	v_sub_f32_e32 v139, v139, v4
	v_sub_f32_e32 v140, v140, v4
	v_sub_f32_e32 v141, v141, v4
	v_sub_f32_e32 v142, v142, v4
	v_sub_f32_e32 v143, v143, v4
	v_sub_f32_e32 v144, v144, v4
	v_sub_f32_e32 v145, v145, v4
	v_sub_f32_e32 v146, v146, v4
	v_sub_f32_e32 v147, v147, v4
	v_sub_f32_e32 v148, v148, v4
	v_sub_f32_e32 v149, v149, v4
	v_sub_f32_e32 v150, v150, v4
	v_sub_f32_e32 v151, v151, v4
	v_sub_f32_e32 v152, v152, v4
	v_sub_f32_e32 v153, v153, v4
	v_sub_f32_e32 v154, v154, v4
	v_sub_f32_e32 v155, v155, v4
	v_sub_f32_e32 v156, v156, v4
	v_sub_f32_e32 v157, v157, v4
	v_sub_f32_e32 v158, v158, v4
	v_sub_f32_e32 v159, v159, v4
	v_xor_b32_e32 v5, 0x80000000, v248
	v_mov_b32_e32 v160, v5
	v_mov_b32_e32 v161, v5
	v_mov_b32_e32 v162, v5
	v_mov_b32_e32 v163, v5
	v_mov_b32_e32 v164, v5
	v_mov_b32_e32 v165, v5
	v_mov_b32_e32 v166, v5
	v_mov_b32_e32 v167, v5
	v_mov_b32_e32 v168, v5
	v_mov_b32_e32 v169, v5
	v_mov_b32_e32 v170, v5
	v_mov_b32_e32 v171, v5
	v_mov_b32_e32 v172, v5
	v_mov_b32_e32 v173, v5
	v_mov_b32_e32 v174, v5
	v_mov_b32_e32 v175, v5
	v_xor_b32_e32 v6, 0x80000000, v4
	v_exp_f32_e32 v6, v6
	s_nop 0
	v_mul_f32_e32 v247, v247, v6
	v_and_b32_e32 v7, 31, v237
	v_lshl_add_u32 v7, v7, 2, v249
	v_cmp_eq_u32_e32 vcc, 0, v252
	s_and_saveexec_b64 s[60:61], vcc
	ds_write_b32 v7, v6
	s_or_b64 exec, exec, s[60:61]

.Lat_norescO_439:
	s_mov_b32 s67, s56
	s_mov_b32 s56, s57
	s_mov_b32 s57, s58
	s_mov_b32 s58, s67
	s_add_u32 s46, s46, 1
	s_cmp_ge_u32 s46, s45
	s_cbranch_scc1 .Lat_drain
	s_lshl_b32 s60, s56, 1
	v_add_u32_e32 v250, s60, v245
	v_mfma_f32_32x32x16_bf16 v[96:111], v[208:211], v[16:19], v[160:175]
	v_add_f32_e32 v247, v247, v128
	v_add_f32_e32 v247, v247, v129
	v_cvt_pk_bf16_f32 v176, v128, v129
	v_cvt_pk_bf16_f32 v177, v130, v131
	v_mfma_f32_32x32x16_bf16 v[112:127], v[212:215], v[16:19], v[160:175]
	v_add_f32_e32 v247, v247, v132
	v_add_f32_e32 v247, v247, v133
	v_cvt_pk_bf16_f32 v178, v132, v133
	v_cvt_pk_bf16_f32 v179, v134, v135
	v_mfma_f32_32x32x16_bf16 v[96:111], v[216:219], v[20:23], v[96:111]
	v_add_f32_e32 v247, v247, v136
	v_add_f32_e32 v247, v247, v137
	v_cvt_pk_bf16_f32 v180, v136, v137
	v_cvt_pk_bf16_f32 v181, v138, v139
	v_mfma_f32_32x32x16_bf16 v[112:127], v[220:223], v[20:23], v[112:127]
	v_add_f32_e32 v247, v247, v140
	v_add_f32_e32 v247, v247, v141
	v_cvt_pk_bf16_f32 v182, v140, v141
	v_cvt_pk_bf16_f32 v183, v142, v143
	v_mfma_f32_32x32x16_bf16 v[96:111], v[224:227], v[24:27], v[96:111]
	v_add_f32_e32 v247, v247, v144
	v_add_f32_e32 v247, v247, v145
	v_cvt_pk_bf16_f32 v184, v144, v145
	v_cvt_pk_bf16_f32 v185, v146, v147
	v_mfma_f32_32x32x16_bf16 v[112:127], v[228:231], v[24:27], v[112:127]
	v_add_f32_e32 v247, v247, v148
	v_add_f32_e32 v247, v247, v149
	v_cvt_pk_bf16_f32 v186, v148, v149
	v_cvt_pk_bf16_f32 v187, v150, v151
	v_mfma_f32_32x32x16_bf16 v[96:111], v[232:235], v[28:31], v[96:111]
	v_add_f32_e32 v247, v247, v152
	v_add_f32_e32 v247, v247, v153
	v_cvt_pk_bf16_f32 v188, v152, v153
	v_cvt_pk_bf16_f32 v189, v154, v155
	ds_read_b64_tr_b16 v[192:193], v250 offset:0
	ds_read_b64_tr_b16 v[194:195], v250 offset:512
	v_mfma_f32_32x32x16_bf16 v[112:127], v[240:243], v[28:31], v[112:127]
	v_add_f32_e32 v247, v247, v156
	v_add_f32_e32 v247, v247, v157
	v_cvt_pk_bf16_f32 v190, v156, v157
	v_cvt_pk_bf16_f32 v191, v158, v159
	ds_read_b64_tr_b16 v[196:197], v250 offset:4096
	ds_read_b64_tr_b16 v[198:199], v250 offset:4608
	s_add_i32 m0, s57, s70
	s_nop 0
	global_load_lds_dwordx4 v238, s[74:75]
	s_add_u32 s74, s74, 0x10000
	s_addc_u32 s75, s75, 0
	s_lshl_b32 s60, s58, 1
	s_add_i32 s60, s60, s71
	s_mov_b32 m0, s60
	s_nop 0
	global_load_lds_dwordx4 v239, s[76:77]
	s_add_u32 s62, s76, 0x80
	s_addc_u32 s63, s77, 0
	s_add_i32 m0, s60, 0x2000
	s_nop 0
	global_load_lds_dwordx4 v239, s[62:63]
	s_add_u32 s76, s76, 0x10000
	s_addc_u32 s77, s77, 0
	s_cmp_lt_u32 s46, s72
	s_cbranch_scc1 .Lat_nomask_920
	s_sub_u32 s60, s46, s72
	s_lshl_b32 s60, s60, 6
	v_lshl_add_u32 v0, v252, 2, s60
	v_sub_u32_e32 v0, v246, v0
	v_mov_b32_e32 v1, 0xff800000
	v_cmp_gt_i32_e64 s[60:61], 0, v0
	v_cmp_gt_i32_e64 s[62:63], 32, v0
	v_cmp_gt_i32_e64 s[64:65], 1, v0
	v_cmp_gt_i32_e64 s[66:67], 33, v0
	v_cndmask_b32_e64 v96, v96, v1, s[60:61]
	v_cmp_gt_i32_e64 s[60:61], 2, v0
	v_cndmask_b32_e64 v112, v112, v1, s[62:63]
	v_cmp_gt_i32_e64 s[62:63], 34, v0
	v_cndmask_b32_e64 v97, v97, v1, s[64:65]
	v_cmp_gt_i32_e64 s[64:65], 3, v0
	v_cndmask_b32_e64 v113, v113, v1, s[66:67]
	v_cmp_gt_i32_e64 s[66:67], 35, v0
	v_cndmask_b32_e64 v98, v98, v1, s[60:61]
	v_cmp_gt_i32_e64 s[60:61], 8, v0
	v_cndmask_b32_e64 v114, v114, v1, s[62:63]
	v_cmp_gt_i32_e64 s[62:63], 40, v0
	v_cndmask_b32_e64 v99, v99, v1, s[64:65]
	v_cmp_gt_i32_e64 s[64:65], 9, v0
	v_cndmask_b32_e64 v115, v115, v1, s[66:67]
	v_cmp_gt_i32_e64 s[66:67], 41, v0
	v_cndmask_b32_e64 v100, v100, v1, s[60:61]
	v_cmp_gt_i32_e64 s[60:61], 10, v0
	v_cndmask_b32_e64 v116, v116, v1, s[62:63]
	v_cmp_gt_i32_e64 s[62:63], 42, v0
	v_cndmask_b32_e64 v101, v101, v1, s[64:65]
	v_cmp_gt_i32_e64 s[64:65], 11, v0
	v_cndmask_b32_e64 v117, v117, v1, s[66:67]
	v_cmp_gt_i32_e64 s[66:67], 43, v0
	v_cndmask_b32_e64 v102, v102, v1, s[60:61]
	v_cmp_gt_i32_e64 s[60:61], 16, v0
	v_cndmask_b32_e64 v118, v118, v1, s[62:63]
	v_cmp_gt_i32_e64 s[62:63], 48, v0
	v_cndmask_b32_e64 v103, v103, v1, s[64:65]
	v_cmp_gt_i32_e64 s[64:65], 17, v0
	v_cndmask_b32_e64 v119, v119, v1, s[66:67]
	v_cmp_gt_i32_e64 s[66:67], 49, v0
	v_cndmask_b32_e64 v104, v104, v1, s[60:61]
	v_cmp_gt_i32_e64 s[60:61], 18, v0
	v_cndmask_b32_e64 v120, v120, v1, s[62:63]
	v_cmp_gt_i32_e64 s[62:63], 50, v0
	v_cndmask_b32_e64 v105, v105, v1, s[64:65]
	v_cmp_gt_i32_e64 s[64:65], 19, v0
	v_cndmask_b32_e64 v121, v121, v1, s[66:67]
	v_cmp_gt_i32_e64 s[66:67], 51, v0
	v_cndmask_b32_e64 v106, v106, v1, s[60:61]
	v_cmp_gt_i32_e64 s[60:61], 24, v0
	v_cndmask_b32_e64 v122, v122, v1, s[62:63]
	v_cmp_gt_i32_e64 s[62:63], 56, v0
	v_cndmask_b32_e64 v107, v107, v1, s[64:65]
	v_cmp_gt_i32_e64 s[64:65], 25, v0
	v_cndmask_b32_e64 v123, v123, v1, s[66:67]
	v_cmp_gt_i32_e64 s[66:67], 57, v0
	v_cndmask_b32_e64 v108, v108, v1, s[60:61]
	v_cmp_gt_i32_e64 s[60:61], 26, v0
	v_cndmask_b32_e64 v124, v124, v1, s[62:63]
	v_cmp_gt_i32_e64 s[62:63], 58, v0
	v_cndmask_b32_e64 v109, v109, v1, s[64:65]
	v_cmp_gt_i32_e64 s[64:65], 27, v0
	v_cndmask_b32_e64 v125, v125, v1, s[66:67]
	v_cmp_gt_i32_e64 s[66:67], 59, v0
	v_cndmask_b32_e64 v110, v110, v1, s[60:61]
	s_nop 1
	v_cndmask_b32_e64 v126, v126, v1, s[62:63]
	v_cndmask_b32_e64 v111, v111, v1, s[64:65]
	v_cndmask_b32_e64 v127, v127, v1, s[66:67]
.Lat_nomask_920:
	ds_read_b64_tr_b16 v[200:201], v250 offset:8192
	ds_read_b64_tr_b16 v[202:203], v250 offset:8704
	ds_read_b64_tr_b16 v[204:205], v250 offset:12288
	ds_read_b64_tr_b16 v[206:207], v250 offset:12800
	s_waitcnt lgkmcnt(4)
	v_mfma_f32_32x32x16_bf16 v[32:47], v[176:179], v[192:195], v[32:47]
	v_max3_f32 v2, v96, v97, v112
	v_max3_f32 v4, v98, v99, v113
	v_max3_f32 v2, v2, v114, v115
	v_add_f32_e32 v247, v247, v130
	v_add_f32_e32 v247, v247, v131
	v_add_f32_e32 v247, v247, v134
	v_mfma_f32_32x32x16_bf16 v[48:63], v[176:179], v[196:199], v[48:63]
	v_max3_f32 v2, v2, v100, v101
	v_max3_f32 v4, v4, v102, v103
	v_max3_f32 v2, v2, v116, v117
	v_add_f32_e32 v247, v247, v135
	v_add_f32_e32 v247, v247, v138
	v_add_f32_e32 v247, v247, v139
	ds_read_b64_tr_b16 v[192:193], v250 offset:1024
	ds_read_b64_tr_b16 v[194:195], v250 offset:1536
	ds_read_b64_tr_b16 v[196:197], v250 offset:5120
	ds_read_b64_tr_b16 v[198:199], v250 offset:5632
	s_waitcnt lgkmcnt(4)
	v_mfma_f32_32x32x16_bf16 v[64:79], v[176:179], v[200:203], v[64:79]
	v_max3_f32 v4, v4, v118, v119
	v_max3_f32 v2, v2, v104, v105
	v_max3_f32 v4, v4, v106, v107
	v_add_f32_e32 v247, v247, v142
	v_add_f32_e32 v247, v247, v143
	v_add_f32_e32 v247, v247, v146
	v_mfma_f32_32x32x16_bf16 v[80:95], v[176:179], v[204:207], v[80:95]
	v_max3_f32 v2, v2, v120, v121
	v_max3_f32 v4, v4, v122, v123
	v_max3_f32 v2, v2, v108, v109
	v_add_f32_e32 v247, v247, v147
	v_add_f32_e32 v247, v247, v150
	v_add_f32_e32 v247, v247, v151
	ds_read_b64_tr_b16 v[200:201], v250 offset:9216
	ds_read_b64_tr_b16 v[202:203], v250 offset:9728
	ds_read_b64_tr_b16 v[204:205], v250 offset:13312
	ds_read_b64_tr_b16 v[206:207], v250 offset:13824
	s_waitcnt lgkmcnt(4)
	v_mfma_f32_32x32x16_bf16 v[32:47], v[180:183], v[192:195], v[32:47]
	v_max3_f32 v4, v4, v110, v111
	v_max3_f32 v2, v2, v124, v125
	v_max3_f32 v4, v4, v126, v127
	v_add_f32_e32 v247, v247, v154
	v_add_f32_e32 v247, v247, v155
	v_mfma_f32_32x32x16_bf16 v[48:63], v[180:183], v[196:199], v[48:63]
	v_max_f32_e32 v2, v2, v4
	v_mov_b32_e32 v4, v2
	s_nop 1
	v_permlane32_swap_b32_e32 v2, v4
	v_max_f32_e32 v2, v2, v4
	v_add_f32_e32 v247, v247, v158
	v_add_f32_e32 v247, v247, v159
	v_mov_b32_e32 v5, 0x41400000
	v_cmp_gt_f32_e32 vcc, v2, v5
	s_mov_b64 s[68:69], vcc
	s_cmp_lg_u64 vcc, 0
	s_cbranch_scc0 .Lat_noresc_855
	v_max_f32_e32 v4, 0, v2
	v_add_f32_e32 v248, v248, v4
	v_sub_f32_e32 v96, v96, v4
	v_sub_f32_e32 v97, v97, v4
	v_sub_f32_e32 v98, v98, v4
	v_sub_f32_e32 v99, v99, v4
	v_sub_f32_e32 v100, v100, v4
	v_sub_f32_e32 v101, v101, v4
	v_sub_f32_e32 v102, v102, v4
	v_sub_f32_e32 v103, v103, v4
	v_sub_f32_e32 v104, v104, v4
	v_sub_f32_e32 v105, v105, v4
	v_sub_f32_e32 v106, v106, v4
	v_sub_f32_e32 v107, v107, v4
	v_sub_f32_e32 v108, v108, v4
	v_sub_f32_e32 v109, v109, v4
	v_sub_f32_e32 v110, v110, v4
	v_sub_f32_e32 v111, v111, v4
	v_sub_f32_e32 v112, v112, v4
	v_sub_f32_e32 v113, v113, v4
	v_sub_f32_e32 v114, v114, v4
	v_sub_f32_e32 v115, v115, v4
	v_sub_f32_e32 v116, v116, v4
	v_sub_f32_e32 v117, v117, v4
	v_sub_f32_e32 v118, v118, v4
	v_sub_f32_e32 v119, v119, v4
	v_sub_f32_e32 v120, v120, v4
	v_sub_f32_e32 v121, v121, v4
	v_sub_f32_e32 v122, v122, v4
	v_sub_f32_e32 v123, v123, v4
	v_sub_f32_e32 v124, v124, v4
	v_sub_f32_e32 v125, v125, v4
	v_sub_f32_e32 v126, v126, v4
	v_sub_f32_e32 v127, v127, v4
	v_xor_b32_e32 v5, 0x80000000, v248
	v_mov_b32_e32 v160, v5
	v_mov_b32_e32 v161, v5
	v_mov_b32_e32 v162, v5
	v_mov_b32_e32 v163, v5
	v_mov_b32_e32 v164, v5
	v_mov_b32_e32 v165, v5
	v_mov_b32_e32 v166, v5
	v_mov_b32_e32 v167, v5
	v_mov_b32_e32 v168, v5
	v_mov_b32_e32 v169, v5
	v_mov_b32_e32 v170, v5
	v_mov_b32_e32 v171, v5
	v_mov_b32_e32 v172, v5
	v_mov_b32_e32 v173, v5
	v_mov_b32_e32 v174, v5
	v_mov_b32_e32 v175, v5
	v_xor_b32_e32 v6, 0x80000000, v4
	v_exp_f32_e32 v6, v6
	s_nop 0
	v_mul_f32_e32 v247, v247, v6
	v_and_b32_e32 v7, 31, v237
	v_lshl_add_u32 v7, v7, 2, v249
	v_cmp_eq_u32_e32 vcc, 0, v252
	s_and_saveexec_b64 s[60:61], vcc
	ds_write_b32 v7, v6
	s_or_b64 exec, exec, s[60:61]
